# v41 + P8 sample-row GEMM also staged through LDS with full-line LDS-DMA
# speedup vs baseline: 1.0312x; 1.0021x over previous
.LBB0_1042:
	v_lshrrev_b32_e32 v132, 6, v236
	v_and_b32_e32 v133, 15, v236
	v_readfirstlane_b32 vcc_lo, v132
	v_bfe_u32 v134, v236, 4, 2
	s_nop 3
	s_mul_i32 s2, vcc_lo, 3
	s_mul_i32 s3, vcc_lo, 2
	s_add_i32 s3, s3, 0
	s_cmp_lt_u32 vcc_lo, 0
	s_cselect_b32 s2, s2, s3
	s_cselect_b32 s3, 3, 2
	s_lshl_b32 s2, s2, 7
	s_lshl_b32 s10, vcc_lo, 14
	s_lshr_b32 vcc_hi, s21, 4
	s_mul_i32 vcc_hi, vcc_hi, 0x20000
	s_add_u32 vcc_hi, vcc_hi, s2
	s_add_u32 s14, s74, 0x5600000
	s_addc_u32 s15, s75, 0
	s_add_u32 s14, s14, vcc_hi
	s_addc_u32 s15, s15, 0
	s_and_b32 vcc_hi, s21, 15
	s_mul_i32 vcc_hi, vcc_hi, 0x20000
	s_add_u32 vcc_hi, vcc_hi, s2
	s_add_u32 s16, s74, 0x2300000
	s_addc_u32 s17, s75, 0
	s_add_u32 s16, s16, vcc_hi
	s_addc_u32 s17, s17, 0
	v_and_b32_e32 v111, 7, v133
	v_xor_b32_e32 v111, v111, v134
	v_lshlrev_b32_e32 v111, 4, v111
	v_lshl_add_u32 v110, v133, 7, v111
	v_add_u32_e32 v110, s10, v110
	v_xor_b32_e32 v111, 64, v110
	v_and_b32_e32 v108, 63, v236
	v_lshrrev_b32_e32 v143, 3, v108
	v_and_b32_e32 v108, 7, v108
	v_xor_b32_e32 v108, v108, v143
	v_mul_u32_u24_e32 v143, 0x800, v143
	v_lshl_add_u32 v108, v108, 4, v143
	v_lshlrev_b32_e32 v132, 14, v132
	v_lshl_or_b32 v132, v133, 8, v132
	v_or_b32_e32 v135, 0, v134
	v_xor_b32_e32 v135, v135, v133
	v_lshl_or_b32 v135, v135, 4, v132
	v_or_b32_e32 v136, 4, v134
	v_xor_b32_e32 v136, v136, v133
	v_lshl_or_b32 v136, v136, 4, v132
	v_or_b32_e32 v137, 8, v134
	v_xor_b32_e32 v137, v137, v133
	v_lshl_or_b32 v137, v137, 4, v132
	v_or_b32_e32 v138, 12, v134
	v_xor_b32_e32 v138, v138, v133
	v_lshl_or_b32 v138, v138, 4, v132
	v_lshrrev_b32_e32 v132, 3, v236
	v_and_b32_e32 v133, 7, v236
	v_lshlrev_b32_e32 v134, 1, v133
	v_bitop3_b32 v134, v134, v132, 15 bitop3:0x78
	v_lshlrev_b32_e32 v134, 4, v134
	v_lshl_or_b32 v139, v132, 8, v134
	v_xor_b32_e32 v140, 16, v139
	v_add_u32_e32 v141, 0x10000, v139
	v_add_u32_e32 v142, 0x10000, v140
	s_lshr_b32 vcc_lo, s21, 4
	s_lshl_b32 vcc_lo, vcc_lo, 6
	s_and_b32 vcc_hi, s21, 15
	s_lshl_b32 vcc_hi, vcc_hi, 6
	v_add_u32_e32 v132, vcc_lo, v132
	v_lshl_add_u32 v133, v133, 3, vcc_hi
	v_lshlrev_b32_e32 v133, 2, v133
	v_lshl_add_u32 v144, v132, 12, v133
	v_lshrrev_b32_e32 v132, 6, v132
	v_add_u32_e32 v132, 8, v132
	v_mul_u32_u24_e32 v132, 0x9000, v132
	v_add_u32_e32 v143, v132, v133
	v_mov_b32_e32 v0, 0
	v_mov_b32_e32 v1, 0
	v_mov_b32_e32 v2, 0
	v_mov_b32_e32 v3, 0
	v_mov_b32_e32 v4, 0
	v_mov_b32_e32 v5, 0
	v_mov_b32_e32 v6, 0
	v_mov_b32_e32 v7, 0
	v_mov_b32_e32 v8, 0
	v_mov_b32_e32 v9, 0
	v_mov_b32_e32 v10, 0
	v_mov_b32_e32 v11, 0
	v_mov_b32_e32 v12, 0
	v_mov_b32_e32 v13, 0
	v_mov_b32_e32 v14, 0
	v_mov_b32_e32 v15, 0
	v_mov_b32_e32 v16, 0
	v_mov_b32_e32 v17, 0
	v_mov_b32_e32 v18, 0
	v_mov_b32_e32 v19, 0
	v_mov_b32_e32 v20, 0
	v_mov_b32_e32 v21, 0
	v_mov_b32_e32 v22, 0
	v_mov_b32_e32 v23, 0
	v_mov_b32_e32 v24, 0
	v_mov_b32_e32 v25, 0
	v_mov_b32_e32 v26, 0
	v_mov_b32_e32 v27, 0
	v_mov_b32_e32 v28, 0
	v_mov_b32_e32 v29, 0
	v_mov_b32_e32 v30, 0
	v_mov_b32_e32 v31, 0
	v_mov_b32_e32 v32, 0
	v_mov_b32_e32 v33, 0
	v_mov_b32_e32 v34, 0
	v_mov_b32_e32 v35, 0
	v_mov_b32_e32 v36, 0
	v_mov_b32_e32 v37, 0
	v_mov_b32_e32 v38, 0
	v_mov_b32_e32 v39, 0
	v_mov_b32_e32 v40, 0
	v_mov_b32_e32 v41, 0
	v_mov_b32_e32 v42, 0
	v_mov_b32_e32 v43, 0
	v_mov_b32_e32 v44, 0
	v_mov_b32_e32 v45, 0
	v_mov_b32_e32 v46, 0
	v_mov_b32_e32 v47, 0
	v_mov_b32_e32 v48, 0
	v_mov_b32_e32 v49, 0
	v_mov_b32_e32 v50, 0
	v_mov_b32_e32 v51, 0
	v_mov_b32_e32 v52, 0
	v_mov_b32_e32 v53, 0
	v_mov_b32_e32 v54, 0
	v_mov_b32_e32 v55, 0
	v_mov_b32_e32 v56, 0
	v_mov_b32_e32 v57, 0
	v_mov_b32_e32 v58, 0
	v_mov_b32_e32 v59, 0
	v_mov_b32_e32 v60, 0
	v_mov_b32_e32 v61, 0
	v_mov_b32_e32 v62, 0
	v_mov_b32_e32 v63, 0
	s_mov_b32 s2, 0
.Lsg2p8_loop:
	s_mov_b64 s[22:23], s[14:15]
	s_mov_b32 m0, s10
	s_nop 0
	global_load_lds_dwordx4 v108, s[22:23]
	s_add_u32 s22, s22, 0x4000
	s_addc_u32 s23, s23, 0
	s_add_i32 m0, s10, 0x400
	s_nop 0
	global_load_lds_dwordx4 v108, s[22:23]
	s_add_u32 s22, s22, 0x4000
	s_addc_u32 s23, s23, 0
	s_add_i32 m0, s10, 0x800
	s_nop 0
	global_load_lds_dwordx4 v108, s[22:23]
	s_add_u32 s22, s22, 0x4000
	s_addc_u32 s23, s23, 0
	s_add_i32 m0, s10, 0xc00
	s_nop 0
	global_load_lds_dwordx4 v108, s[22:23]
	s_add_u32 s22, s22, 0x4000
	s_addc_u32 s23, s23, 0
	s_add_i32 m0, s10, 0x1000
	s_nop 0
	global_load_lds_dwordx4 v108, s[22:23]
	s_add_u32 s22, s22, 0x4000
	s_addc_u32 s23, s23, 0
	s_add_i32 m0, s10, 0x1400
	s_nop 0
	global_load_lds_dwordx4 v108, s[22:23]
	s_add_u32 s22, s22, 0x4000
	s_addc_u32 s23, s23, 0
	s_add_i32 m0, s10, 0x1800
	s_nop 0
	global_load_lds_dwordx4 v108, s[22:23]
	s_add_u32 s22, s22, 0x4000
	s_addc_u32 s23, s23, 0
	s_add_i32 m0, s10, 0x1c00
	s_nop 0
	global_load_lds_dwordx4 v108, s[22:23]
	s_mov_b64 s[22:23], s[16:17]
	s_add_i32 m0, s10, 0x2000
	s_nop 0
	global_load_lds_dwordx4 v108, s[22:23]
	s_add_u32 s22, s22, 0x4000
	s_addc_u32 s23, s23, 0
	s_add_i32 m0, s10, 0x2400
	s_nop 0
	global_load_lds_dwordx4 v108, s[22:23]
	s_add_u32 s22, s22, 0x4000
	s_addc_u32 s23, s23, 0
	s_add_i32 m0, s10, 0x2800
	s_nop 0
	global_load_lds_dwordx4 v108, s[22:23]
	s_add_u32 s22, s22, 0x4000
	s_addc_u32 s23, s23, 0
	s_add_i32 m0, s10, 0x2c00
	s_nop 0
	global_load_lds_dwordx4 v108, s[22:23]
	s_add_u32 s22, s22, 0x4000
	s_addc_u32 s23, s23, 0
	s_add_i32 m0, s10, 0x3000
	s_nop 0
	global_load_lds_dwordx4 v108, s[22:23]
	s_add_u32 s22, s22, 0x4000
	s_addc_u32 s23, s23, 0
	s_add_i32 m0, s10, 0x3400
	s_nop 0
	global_load_lds_dwordx4 v108, s[22:23]
	s_add_u32 s22, s22, 0x4000
	s_addc_u32 s23, s23, 0
	s_add_i32 m0, s10, 0x3800
	s_nop 0
	global_load_lds_dwordx4 v108, s[22:23]
	s_add_u32 s22, s22, 0x4000
	s_addc_u32 s23, s23, 0
	s_add_i32 m0, s10, 0x3c00
	s_nop 0
	global_load_lds_dwordx4 v108, s[22:23]
	s_add_u32 s14, s14, 0x80
	s_addc_u32 s15, s15, 0
	s_add_u32 s16, s16, 0x80
	s_addc_u32 s17, s17, 0
	s_waitcnt vmcnt(0)
	ds_read_b128 v[64:67], v110
	ds_read_b128 v[68:71], v110 offset:2048
	ds_read_b128 v[72:75], v110 offset:4096
	ds_read_b128 v[76:79], v110 offset:6144
	ds_read_b128 v[96:99], v110 offset:8192
	ds_read_b128 v[100:103], v110 offset:10240
	ds_read_b128 v[104:107], v110 offset:12288
	ds_read_b128 v[112:115], v110 offset:14336
	ds_read_b128 v[80:83], v111
	ds_read_b128 v[84:87], v111 offset:2048
	ds_read_b128 v[88:91], v111 offset:4096
	ds_read_b128 v[92:95], v111 offset:6144
	ds_read_b128 v[116:119], v111 offset:8192
	ds_read_b128 v[120:123], v111 offset:10240
	ds_read_b128 v[124:127], v111 offset:12288
	ds_read_b128 v[128:131], v111 offset:14336
	s_waitcnt lgkmcnt(8)
	v_mfma_f32_16x16x32_bf16 v[0:3], v[96:99], v[64:67], v[0:3]
	v_mfma_f32_16x16x32_bf16 v[4:7], v[100:103], v[64:67], v[4:7]
	v_mfma_f32_16x16x32_bf16 v[8:11], v[104:107], v[64:67], v[8:11]
	v_mfma_f32_16x16x32_bf16 v[12:15], v[112:115], v[64:67], v[12:15]
	v_mfma_f32_16x16x32_bf16 v[16:19], v[96:99], v[68:71], v[16:19]
	v_mfma_f32_16x16x32_bf16 v[20:23], v[100:103], v[68:71], v[20:23]
	v_mfma_f32_16x16x32_bf16 v[24:27], v[104:107], v[68:71], v[24:27]
	v_mfma_f32_16x16x32_bf16 v[28:31], v[112:115], v[68:71], v[28:31]
	v_mfma_f32_16x16x32_bf16 v[32:35], v[96:99], v[72:75], v[32:35]
	v_mfma_f32_16x16x32_bf16 v[36:39], v[100:103], v[72:75], v[36:39]
	v_mfma_f32_16x16x32_bf16 v[40:43], v[104:107], v[72:75], v[40:43]
	v_mfma_f32_16x16x32_bf16 v[44:47], v[112:115], v[72:75], v[44:47]
	v_mfma_f32_16x16x32_bf16 v[48:51], v[96:99], v[76:79], v[48:51]
	v_mfma_f32_16x16x32_bf16 v[52:55], v[100:103], v[76:79], v[52:55]
	v_mfma_f32_16x16x32_bf16 v[56:59], v[104:107], v[76:79], v[56:59]
	v_mfma_f32_16x16x32_bf16 v[60:63], v[112:115], v[76:79], v[60:63]
	s_waitcnt lgkmcnt(0)
	v_mfma_f32_16x16x32_bf16 v[0:3], v[116:119], v[80:83], v[0:3]
	v_mfma_f32_16x16x32_bf16 v[4:7], v[120:123], v[80:83], v[4:7]
	v_mfma_f32_16x16x32_bf16 v[8:11], v[124:127], v[80:83], v[8:11]
	v_mfma_f32_16x16x32_bf16 v[12:15], v[128:131], v[80:83], v[12:15]
	v_mfma_f32_16x16x32_bf16 v[16:19], v[116:119], v[84:87], v[16:19]
	v_mfma_f32_16x16x32_bf16 v[20:23], v[120:123], v[84:87], v[20:23]
	v_mfma_f32_16x16x32_bf16 v[24:27], v[124:127], v[84:87], v[24:27]
	v_mfma_f32_16x16x32_bf16 v[28:31], v[128:131], v[84:87], v[28:31]
	v_mfma_f32_16x16x32_bf16 v[32:35], v[116:119], v[88:91], v[32:35]
	v_mfma_f32_16x16x32_bf16 v[36:39], v[120:123], v[88:91], v[36:39]
	v_mfma_f32_16x16x32_bf16 v[40:43], v[124:127], v[88:91], v[40:43]
	v_mfma_f32_16x16x32_bf16 v[44:47], v[128:131], v[88:91], v[44:47]
	v_mfma_f32_16x16x32_bf16 v[48:51], v[116:119], v[92:95], v[48:51]
	v_mfma_f32_16x16x32_bf16 v[52:55], v[120:123], v[92:95], v[52:55]
	v_mfma_f32_16x16x32_bf16 v[56:59], v[124:127], v[92:95], v[56:59]
	v_mfma_f32_16x16x32_bf16 v[60:63], v[128:131], v[92:95], v[60:63]
	s_add_i32 s2, s2, 1
	s_cmp_lt_u32 s2, s3
	s_cbranch_scc1 .Lsg2p8_loop
	s_add_u32 s14, s74, 0x5000
	s_addc_u32 s15, s75, 0
	s_add_u32 s16, s72, 0x4000000
	s_addc_u32 s17, s73, 0
	s_nop 7
	s_nop 7
	global_load_dwordx4 v[64:67], v143, s[14:15]
	global_load_dwordx4 v[68:71], v143, s[14:15] offset:16
	global_load_dwordx4 v[72:75], v144, s[16:17]
	global_load_dwordx4 v[76:79], v144, s[16:17] offset:16
	ds_write_b128 v135, v[0:3]
	ds_write_b128 v136, v[4:7]
	ds_write_b128 v137, v[8:11]
	ds_write_b128 v138, v[12:15]
	ds_write_b128 v135, v[16:19] offset:4096
	ds_write_b128 v136, v[20:23] offset:4096
	ds_write_b128 v137, v[24:27] offset:4096
	ds_write_b128 v138, v[28:31] offset:4096
	ds_write_b128 v135, v[32:35] offset:8192
	ds_write_b128 v136, v[36:39] offset:8192
	ds_write_b128 v137, v[40:43] offset:8192
	ds_write_b128 v138, v[44:47] offset:8192
	ds_write_b128 v135, v[48:51] offset:12288
	ds_write_b128 v136, v[52:55] offset:12288
	ds_write_b128 v137, v[56:59] offset:12288
	ds_write_b128 v138, v[60:63] offset:12288
	s_add_u32 s16, s72, 0x4000000
	s_addc_u32 s17, s73, 0
	s_waitcnt lgkmcnt(0)
	s_barrier
	ds_read_b128 v[0:3], v139
	ds_read_b128 v[32:35], v140
	ds_read_b128 v[4:7], v139 offset:16384
	ds_read_b128 v[36:39], v140 offset:16384
	ds_read_b128 v[8:11], v139 offset:32768
	ds_read_b128 v[40:43], v140 offset:32768
	ds_read_b128 v[12:15], v139 offset:49152
	ds_read_b128 v[44:47], v140 offset:49152
	ds_read_b128 v[16:19], v141
	ds_read_b128 v[48:51], v142
	ds_read_b128 v[20:23], v141 offset:16384
	ds_read_b128 v[52:55], v142 offset:16384
	ds_read_b128 v[24:27], v141 offset:32768
	ds_read_b128 v[56:59], v142 offset:32768
	ds_read_b128 v[28:31], v141 offset:49152
	ds_read_b128 v[60:63], v142 offset:49152
	s_waitcnt vmcnt(0)
	s_waitcnt lgkmcnt(14)
	v_pk_add_f32 v[0:1], v[0:1], 0 op_sel_hi:[1,0]
	v_pk_add_f32 v[2:3], v[2:3], 0 op_sel_hi:[1,0]
	v_pk_add_f32 v[32:33], v[32:33], 0 op_sel_hi:[1,0]
	v_pk_add_f32 v[34:35], v[34:35], 0 op_sel_hi:[1,0]
	s_waitcnt lgkmcnt(12)
	v_pk_add_f32 v[0:1], v[0:1], v[4:5]
	v_pk_add_f32 v[2:3], v[2:3], v[6:7]
	v_pk_add_f32 v[32:33], v[32:33], v[36:37]
	v_pk_add_f32 v[34:35], v[34:35], v[38:39]
	s_waitcnt lgkmcnt(10)
	v_pk_add_f32 v[0:1], v[0:1], v[8:9]
	v_pk_add_f32 v[2:3], v[2:3], v[10:11]
	v_pk_add_f32 v[32:33], v[32:33], v[40:41]
	v_pk_add_f32 v[34:35], v[34:35], v[42:43]
	s_waitcnt lgkmcnt(8)
	v_pk_add_f32 v[0:1], v[0:1], v[12:13]
	v_pk_add_f32 v[2:3], v[2:3], v[14:15]
	v_pk_add_f32 v[32:33], v[32:33], v[44:45]
	v_pk_add_f32 v[34:35], v[34:35], v[46:47]
	s_waitcnt lgkmcnt(6)
	v_pk_add_f32 v[0:1], v[0:1], v[16:17]
	v_pk_add_f32 v[2:3], v[2:3], v[18:19]
	v_pk_add_f32 v[32:33], v[32:33], v[48:49]
	v_pk_add_f32 v[34:35], v[34:35], v[50:51]
	s_waitcnt lgkmcnt(4)
	v_pk_add_f32 v[0:1], v[0:1], v[20:21]
	v_pk_add_f32 v[2:3], v[2:3], v[22:23]
	v_pk_add_f32 v[32:33], v[32:33], v[52:53]
	v_pk_add_f32 v[34:35], v[34:35], v[54:55]
	s_waitcnt lgkmcnt(2)
	v_pk_add_f32 v[0:1], v[0:1], v[24:25]
	v_pk_add_f32 v[2:3], v[2:3], v[26:27]
	v_pk_add_f32 v[32:33], v[32:33], v[56:57]
	v_pk_add_f32 v[34:35], v[34:35], v[58:59]
	s_waitcnt lgkmcnt(0)
	v_pk_add_f32 v[0:1], v[0:1], v[28:29]
	v_pk_add_f32 v[2:3], v[2:3], v[30:31]
	v_pk_add_f32 v[32:33], v[32:33], v[60:61]
	v_pk_add_f32 v[34:35], v[34:35], v[62:63]
	v_pk_fma_f32 v[0:1], v[64:65], v[0:1], v[72:73]
	v_pk_fma_f32 v[2:3], v[66:67], v[2:3], v[74:75]
	v_pk_fma_f32 v[32:33], v[68:69], v[32:33], v[76:77]
	v_pk_fma_f32 v[34:35], v[70:71], v[34:35], v[78:79]
	global_store_dwordx4 v144, v[0:3], s[16:17]
	global_store_dwordx4 v144, v[32:35], s[16:17] offset:16
	s_barrier
	s_add_i32 s21, s21, s78
	s_add_i32 s4, s4, s5
	s_add_i32 s12, s12, s13
	s_cmpk_gt_i32 s21, 0xff
	s_cbranch_scc0 .LBB0_1042
